# P5 start staggered 20us for odd-XCD workgroups to interleave gate-load bursts with the other half's K-loops
# baseline (speedup 1.0000x reference)
.LBB0_362:
	v_lshrrev_b32_e32 v18, 1, v2
	v_and_b32_e32 v18, 24, v18
	v_and_b32_e32 v9, 15, v2
	v_lshlrev_b32_e32 v19, 1, v18
	v_lshlrev_b32_e32 v2, 2, v2
	v_lshl_or_b32 v197, s0, 6, v9
	v_lshl_or_b32 v9, v9, 6, v19
	s_lshl_b32 s0, s0, 13
	v_and_b32_e32 v2, 32, v2
	v_lshl_add_u64 v[10:11], s[52:53], 0, v[194:195]
	v_mov_b32_e32 v211, v195
	v_bitop3_b32 v199, v9, s0, v2 bitop3:0xde
	s_lshl_b32 s0, s1, 5
	s_add_i32 s78, s34, 0x18000
	v_lshl_add_u64 v[12:13], s[52:53], 0, v[210:211]
	v_mov_b32_e32 v207, v195
	s_and_b32 s7, s0, 0x60
	v_lshl_add_u64 v[10:11], v[10:11], 0, s[76:77]
	s_mov_b32 m0, s78
	s_add_i32 s79, s34, 0x1a000
	v_lshl_add_u64 v[14:15], s[8:9], 0, v[206:207]
	v_mov_b32_e32 v209, v195
	s_lshl_b32 s0, s7, 7
	s_waitcnt vmcnt(4)
	s_barrier
	global_load_lds_dwordx4 v[10:11], off
	v_lshl_add_u64 v[10:11], v[12:13], 0, s[76:77]
	s_mov_b32 m0, s79
	s_add_i32 s26, s34, 0x8000
	s_add_i32 s4, s34, 0xa000
	v_lshl_add_u64 v[16:17], s[8:9], 0, v[208:209]
	v_bitop3_b32 v201, v9, s0, v2 bitop3:0xde
	global_load_lds_dwordx4 v[10:11], off
	v_lshl_add_u64 v[10:11], v[14:15], 0, s[76:77]
	s_mov_b32 m0, s26
	s_add_u32 s0, s52, 0x40080
	global_load_lds_dwordx4 v[10:11], off
	v_lshl_add_u64 v[10:11], v[16:17], 0, s[76:77]
	s_mov_b32 m0, s4
	s_addc_u32 s1, s53, 0
	s_add_i32 s5, s34, 0x1c000
	global_load_lds_dwordx4 v[10:11], off
	v_lshl_add_u64 v[10:11], s[0:1], 0, v[194:195]
	s_mov_b32 m0, s5
	s_add_i32 s58, s34, 0x1e000
	global_load_lds_dwordx4 v[10:11], off
	v_lshl_add_u64 v[10:11], s[0:1], 0, v[210:211]
	s_mov_b32 m0, s58
	v_lshlrev_b32_e32 v2, 14, v3
	global_load_lds_dwordx4 v[10:11], off
	v_and_b32_e32 v2, 0xffff8000, v2
	v_lshl_add_u32 v2, v4, 11, v2
	v_and_b32_e32 v3, 1, v3
	v_lshl_or_b32 v2, v3, 6, v2
	v_lshl_add_u32 v212, v5, 1, v2
	v_lshlrev_b32_e32 v2, 14, v6
	v_and_b32_e32 v2, 0xffff8000, v2
	v_lshl_add_u32 v2, v7, 11, v2
	v_and_b32_e32 v3, 1, v6
	s_waitcnt vmcnt(6)
	v_lshl_or_b32 v2, v3, 6, v2
	v_lshl_add_u32 v214, v8, 1, v2
	v_mov_b32_e32 v2, 0
	s_lshr_b32 s59, s33, 3
	v_or_b32_e32 v203, s7, v18
	v_mov_b32_e32 v213, v195
	v_mov_b32_e32 v215, v195
	s_mov_b32 s95, 0
	s_mov_b32 s94, 0
	v_mov_b32_e32 v3, v2
	v_mov_b32_e32 v4, v2
	v_mov_b32_e32 v5, v2
	v_mov_b32_e32 v6, v2
	v_mov_b32_e32 v7, v2
	v_mov_b32_e32 v8, v2
	v_mov_b32_e32 v9, v2
	v_mov_b32_e32 v10, v2
	v_mov_b32_e32 v11, v2
	v_mov_b32_e32 v12, v2
	v_mov_b32_e32 v13, v2
	v_mov_b32_e32 v14, v2
	v_mov_b32_e32 v15, v2
	v_mov_b32_e32 v16, v2
	v_mov_b32_e32 v17, v2
	v_mov_b32_e32 v18, v2
	v_mov_b32_e32 v19, v2
	v_mov_b32_e32 v20, v2
	v_mov_b32_e32 v21, v2
	v_mov_b32_e32 v22, v2
	v_mov_b32_e32 v23, v2
	v_mov_b32_e32 v24, v2
	v_mov_b32_e32 v25, v2
	v_mov_b32_e32 v26, v2
	v_mov_b32_e32 v27, v2
	v_mov_b32_e32 v28, v2
	v_mov_b32_e32 v29, v2
	v_mov_b32_e32 v30, v2
	v_mov_b32_e32 v31, v2
	v_mov_b32_e32 v32, v2
	v_mov_b32_e32 v33, v2
	v_mov_b32_e32 v34, v2
	v_mov_b32_e32 v35, v2
	v_mov_b32_e32 v36, v2
	v_mov_b32_e32 v37, v2
	v_mov_b32_e32 v38, v2
	v_mov_b32_e32 v39, v2
	v_mov_b32_e32 v40, v2
	v_mov_b32_e32 v41, v2
	v_mov_b32_e32 v42, v2
	v_mov_b32_e32 v43, v2
	v_mov_b32_e32 v44, v2
	v_mov_b32_e32 v45, v2
	v_mov_b32_e32 v46, v2
	v_mov_b32_e32 v47, v2
	v_mov_b32_e32 v48, v2
	v_mov_b32_e32 v49, v2
	v_mov_b32_e32 v50, v2
	v_mov_b32_e32 v51, v2
	v_mov_b32_e32 v52, v2
	v_mov_b32_e32 v53, v2
	v_mov_b32_e32 v54, v2
	v_mov_b32_e32 v55, v2
	v_mov_b32_e32 v56, v2
	v_mov_b32_e32 v57, v2
	v_mov_b32_e32 v58, v2
	v_mov_b32_e32 v59, v2
	v_mov_b32_e32 v60, v2
	v_mov_b32_e32 v61, v2
	v_mov_b32_e32 v62, v2
	v_mov_b32_e32 v63, v2
	v_mov_b32_e32 v64, v2
	v_mov_b32_e32 v65, v2
	v_mov_b32_e32 v66, v2
	v_mov_b32_e32 v67, v2
	v_mov_b32_e32 v68, v2
	v_mov_b32_e32 v69, v2
	v_mov_b32_e32 v70, v2
	v_mov_b32_e32 v71, v2
	v_mov_b32_e32 v72, v2
	v_mov_b32_e32 v73, v2
	v_mov_b32_e32 v74, v2
	v_mov_b32_e32 v75, v2
	v_mov_b32_e32 v76, v2
	v_mov_b32_e32 v77, v2
	v_mov_b32_e32 v78, v2
	v_mov_b32_e32 v79, v2
	v_mov_b32_e32 v80, v2
	v_mov_b32_e32 v81, v2
	v_mov_b32_e32 v82, v2
	v_mov_b32_e32 v83, v2
	v_mov_b32_e32 v84, v2
	v_mov_b32_e32 v85, v2
	v_mov_b32_e32 v86, v2
	v_mov_b32_e32 v87, v2
	v_mov_b32_e32 v88, v2
	v_mov_b32_e32 v89, v2
	v_mov_b32_e32 v90, v2
	v_mov_b32_e32 v91, v2
	v_mov_b32_e32 v92, v2
	v_mov_b32_e32 v93, v2
	v_mov_b32_e32 v94, v2
	v_mov_b32_e32 v95, v2
	v_mov_b32_e32 v96, v2
	v_mov_b32_e32 v97, v2
	v_mov_b32_e32 v98, v2
	v_mov_b32_e32 v99, v2
	v_mov_b32_e32 v100, v2
	v_mov_b32_e32 v101, v2
	v_mov_b32_e32 v102, v2
	v_mov_b32_e32 v103, v2
	v_mov_b32_e32 v104, v2
	v_mov_b32_e32 v105, v2
	v_mov_b32_e32 v106, v2
	v_mov_b32_e32 v107, v2
	v_mov_b32_e32 v108, v2
	v_mov_b32_e32 v109, v2
	v_mov_b32_e32 v110, v2
	v_mov_b32_e32 v111, v2
	v_mov_b32_e32 v112, v2
	v_mov_b32_e32 v113, v2
	v_mov_b32_e32 v114, v2
	v_mov_b32_e32 v115, v2
	v_mov_b32_e32 v116, v2
	v_mov_b32_e32 v117, v2
	v_mov_b32_e32 v118, v2
	v_mov_b32_e32 v119, v2
	v_mov_b32_e32 v120, v2
	v_mov_b32_e32 v121, v2
	v_mov_b32_e32 v122, v2
	v_mov_b32_e32 v123, v2
	v_mov_b32_e32 v124, v2
	v_mov_b32_e32 v125, v2
	v_mov_b32_e32 v126, v2
	v_mov_b32_e32 v127, v2
	v_mov_b32_e32 v128, v2
	v_mov_b32_e32 v129, v2
	s_bitcmp1_b32 s92, 0
	s_cbranch_scc0 .Lstg_skip_p5
	s_memrealtime s[98:99]
	s_waitcnt lgkmcnt(0)

.Lstg_skip_p5:
	s_mov_b64 s[82:83], s[52:53]
	s_mov_b64 s[80:81], s[8:9]
	s_barrier
	s_branch .LBB0_365
